# q/k rope epilogue of proj GEMM (both layers) de-serialised: rope-table loads batched 8 rows ahead with counted vmcnt instead of load-vmcnt0-store per row
# speedup vs baseline: 1.0115x; 1.0062x over previous
.LBB0_365:
	s_cmpk_lt_u32 s65, 0x200
	s_cselect_b64 vcc, -1, 0
	s_and_b64 s[20:21], vcc, exec
	s_cselect_b32 s8, 0, 0x1000000
	s_add_u32 s20, s86, s8
	s_addc_u32 s21, s87, 0
	v_lshl_or_b32 v162, v200, 2, v166
	v_lshlrev_b32_e32 v164, 1, v167
	v_lshl_add_u64 v[160:161], s[20:21], 0, v[164:165]
	v_cndmask_b32_e32 v166, 1.0, v194, vcc
	v_lshlrev_b32_e32 v164, 1, v199
	v_ashrrev_i32_e32 v163, 31, v162
	v_lshlrev_b64 v[168:169], 10, v[162:163]
	v_lshl_add_u64 v[168:169], v[160:161], 0, v[168:169]
	v_lshl_add_u64 v[168:169], v[168:169], 0, v[164:165]
	s_mov_b32 s8, 0x3ffe0
	v_lshlrev_b32_e32 v163, 5, v162
	v_and_or_b32 v163, v163, s8, v199
	v_lshlrev_b32_e32 v163, 2, v163
	s_mov_b32 s20, 0x2000
	s_mov_b32 s21, 0
	global_load_dword v221, v163, s[4:5]
	global_load_dword v229, v163, s[6:7]
	global_load_dword v222, v163, s[4:5] offset:128
	global_load_dword v230, v163, s[6:7] offset:128
	global_load_dword v223, v163, s[4:5] offset:256
	global_load_dword v231, v163, s[6:7] offset:256
	global_load_dword v224, v163, s[4:5] offset:384
	global_load_dword v232, v163, s[6:7] offset:384
	global_load_dword v225, v163, s[4:5] offset:1024
	global_load_dword v233, v163, s[6:7] offset:1024
	global_load_dword v226, v163, s[4:5] offset:1152
	global_load_dword v234, v163, s[6:7] offset:1152
	global_load_dword v227, v163, s[4:5] offset:1280
	global_load_dword v235, v163, s[6:7] offset:1280
	global_load_dword v228, v163, s[4:5] offset:1408
	global_load_dword v236, v163, s[6:7] offset:1408
	global_load_dword v237, v163, s[4:5] offset:2048
	global_load_dword v245, v163, s[6:7] offset:2048
	global_load_dword v238, v163, s[4:5] offset:2176
	global_load_dword v246, v163, s[6:7] offset:2176
	global_load_dword v239, v163, s[4:5] offset:2304
	global_load_dword v247, v163, s[6:7] offset:2304
	global_load_dword v240, v163, s[4:5] offset:2432
	global_load_dword v248, v163, s[6:7] offset:2432
	global_load_dword v241, v163, s[4:5] offset:3072
	global_load_dword v249, v163, s[6:7] offset:3072
	global_load_dword v242, v163, s[4:5] offset:3200
	global_load_dword v250, v163, s[6:7] offset:3200
	global_load_dword v243, v163, s[4:5] offset:3328
	global_load_dword v251, v163, s[6:7] offset:3328
	global_load_dword v244, v163, s[4:5] offset:3456
	global_load_dword v253, v163, s[6:7] offset:3456
	s_waitcnt vmcnt(16)
	v_mul_f32_e32 v160, v96, v229
	v_mul_f32_e32 v161, v112, v229
	v_fma_f32 v160, v112, v221, -v160
	v_fmac_f32_e32 v161, v96, v221
	v_mul_f32_e32 v160, v166, v160
	v_mul_f32_e32 v161, v166, v161
	v_cvt_pk_bf16_f32 v160, v160, s0
	v_cvt_pk_bf16_f32 v161, v161, s0
	global_store_short v[168:169], v160, off
	global_store_short v[168:169], v161, off offset:64
	v_mul_f32_e32 v162, v97, v230
	v_mul_f32_e32 v164, v113, v230
	v_fma_f32 v162, v113, v222, -v162
	v_fmac_f32_e32 v164, v97, v222
	v_mul_f32_e32 v162, v166, v162
	v_mul_f32_e32 v164, v166, v164
	v_cvt_pk_bf16_f32 v162, v162, s0
	v_cvt_pk_bf16_f32 v164, v164, s0
	global_store_short v[168:169], v162, off offset:1024
	global_store_short v[168:169], v164, off offset:1088
	v_mul_f32_e32 v167, v98, v231
	v_mul_f32_e32 v171, v114, v231
	v_fma_f32 v167, v114, v223, -v167
	v_fmac_f32_e32 v171, v98, v223
	v_mul_f32_e32 v167, v166, v167
	v_mul_f32_e32 v171, v166, v171
	v_cvt_pk_bf16_f32 v167, v167, s0
	v_cvt_pk_bf16_f32 v171, v171, s0
	global_store_short v[168:169], v167, off offset:2048
	global_store_short v[168:169], v171, off offset:2112
	v_mul_f32_e32 v160, v99, v232
	v_mul_f32_e32 v161, v115, v232
	v_fma_f32 v160, v115, v224, -v160
	v_fmac_f32_e32 v161, v99, v224
	v_mul_f32_e32 v160, v166, v160
	v_mul_f32_e32 v161, v166, v161
	v_cvt_pk_bf16_f32 v160, v160, s0
	v_cvt_pk_bf16_f32 v161, v161, s0
	global_store_short v[168:169], v160, off offset:3072
	global_store_short v[168:169], v161, off offset:3136
	v_lshl_add_u64 v[168:169], v[168:169], 0, s[20:21]
	v_mul_f32_e32 v162, v100, v233
	v_mul_f32_e32 v164, v116, v233
	v_fma_f32 v162, v116, v225, -v162
	v_fmac_f32_e32 v164, v100, v225
	v_mul_f32_e32 v162, v166, v162
	v_mul_f32_e32 v164, v166, v164
	v_cvt_pk_bf16_f32 v162, v162, s0
	v_cvt_pk_bf16_f32 v164, v164, s0
	global_store_short v[168:169], v162, off
	global_store_short v[168:169], v164, off offset:64
	v_mul_f32_e32 v167, v101, v234
	v_mul_f32_e32 v171, v117, v234
	v_fma_f32 v167, v117, v226, -v167
	v_fmac_f32_e32 v171, v101, v226
	v_mul_f32_e32 v167, v166, v167
	v_mul_f32_e32 v171, v166, v171
	v_cvt_pk_bf16_f32 v167, v167, s0
	v_cvt_pk_bf16_f32 v171, v171, s0
	global_store_short v[168:169], v167, off offset:1024
	global_store_short v[168:169], v171, off offset:1088
	v_mul_f32_e32 v160, v102, v235
	v_mul_f32_e32 v161, v118, v235
	v_fma_f32 v160, v118, v227, -v160
	v_fmac_f32_e32 v161, v102, v227
	v_mul_f32_e32 v160, v166, v160
	v_mul_f32_e32 v161, v166, v161
	v_cvt_pk_bf16_f32 v160, v160, s0
	v_cvt_pk_bf16_f32 v161, v161, s0
	global_store_short v[168:169], v160, off offset:2048
	global_store_short v[168:169], v161, off offset:2112
	v_mul_f32_e32 v162, v103, v236
	v_mul_f32_e32 v164, v119, v236
	v_fma_f32 v162, v119, v228, -v162
	v_fmac_f32_e32 v164, v103, v228
	v_mul_f32_e32 v162, v166, v162
	v_mul_f32_e32 v164, v166, v164
	v_cvt_pk_bf16_f32 v162, v162, s0
	v_cvt_pk_bf16_f32 v164, v164, s0
	global_store_short v[168:169], v162, off offset:3072
	global_store_short v[168:169], v164, off offset:3136
	v_lshl_add_u64 v[168:169], v[168:169], 0, s[20:21]
	v_add_u32_e32 v170, 0x1000, v163
	global_load_dword v221, v170, s[4:5]
	global_load_dword v229, v170, s[6:7]
	global_load_dword v222, v170, s[4:5] offset:128
	global_load_dword v230, v170, s[6:7] offset:128
	global_load_dword v223, v170, s[4:5] offset:256
	global_load_dword v231, v170, s[6:7] offset:256
	global_load_dword v224, v170, s[4:5] offset:384
	global_load_dword v232, v170, s[6:7] offset:384
	global_load_dword v225, v170, s[4:5] offset:1024
	global_load_dword v233, v170, s[6:7] offset:1024
	global_load_dword v226, v170, s[4:5] offset:1152
	global_load_dword v234, v170, s[6:7] offset:1152
	global_load_dword v227, v170, s[4:5] offset:1280
	global_load_dword v235, v170, s[6:7] offset:1280
	global_load_dword v228, v170, s[4:5] offset:1408
	global_load_dword v236, v170, s[6:7] offset:1408
	s_waitcnt vmcnt(32)
	v_mul_f32_e32 v160, v104, v245
	v_mul_f32_e32 v161, v120, v245
	v_fma_f32 v160, v120, v237, -v160
	v_fmac_f32_e32 v161, v104, v237
	v_mul_f32_e32 v160, v166, v160
	v_mul_f32_e32 v161, v166, v161
	v_cvt_pk_bf16_f32 v160, v160, s0
	v_cvt_pk_bf16_f32 v161, v161, s0
	global_store_short v[168:169], v160, off
	global_store_short v[168:169], v161, off offset:64
	v_mul_f32_e32 v162, v105, v246
	v_mul_f32_e32 v164, v121, v246
	v_fma_f32 v162, v121, v238, -v162
	v_fmac_f32_e32 v164, v105, v238
	v_mul_f32_e32 v162, v166, v162
	v_mul_f32_e32 v164, v166, v164
	v_cvt_pk_bf16_f32 v162, v162, s0
	v_cvt_pk_bf16_f32 v164, v164, s0
	global_store_short v[168:169], v162, off offset:1024
	global_store_short v[168:169], v164, off offset:1088
	v_mul_f32_e32 v167, v106, v247
	v_mul_f32_e32 v171, v122, v247
	v_fma_f32 v167, v122, v239, -v167
	v_fmac_f32_e32 v171, v106, v239
	v_mul_f32_e32 v167, v166, v167
	v_mul_f32_e32 v171, v166, v171
	v_cvt_pk_bf16_f32 v167, v167, s0
	v_cvt_pk_bf16_f32 v171, v171, s0
	global_store_short v[168:169], v167, off offset:2048
	global_store_short v[168:169], v171, off offset:2112
	v_mul_f32_e32 v160, v107, v248
	v_mul_f32_e32 v161, v123, v248
	v_fma_f32 v160, v123, v240, -v160
	v_fmac_f32_e32 v161, v107, v240
	v_mul_f32_e32 v160, v166, v160
	v_mul_f32_e32 v161, v166, v161
	v_cvt_pk_bf16_f32 v160, v160, s0
	v_cvt_pk_bf16_f32 v161, v161, s0
	global_store_short v[168:169], v160, off offset:3072
	global_store_short v[168:169], v161, off offset:3136
	v_lshl_add_u64 v[168:169], v[168:169], 0, s[20:21]
	v_mul_f32_e32 v162, v108, v249
	v_mul_f32_e32 v164, v124, v249
	v_fma_f32 v162, v124, v241, -v162
	v_fmac_f32_e32 v164, v108, v241
	v_mul_f32_e32 v162, v166, v162
	v_mul_f32_e32 v164, v166, v164
	v_cvt_pk_bf16_f32 v162, v162, s0
	v_cvt_pk_bf16_f32 v164, v164, s0
	global_store_short v[168:169], v162, off
	global_store_short v[168:169], v164, off offset:64
	v_mul_f32_e32 v167, v109, v250
	v_mul_f32_e32 v171, v125, v250
	v_fma_f32 v167, v125, v242, -v167
	v_fmac_f32_e32 v171, v109, v242
	v_mul_f32_e32 v167, v166, v167
	v_mul_f32_e32 v171, v166, v171
	v_cvt_pk_bf16_f32 v167, v167, s0
	v_cvt_pk_bf16_f32 v171, v171, s0
	global_store_short v[168:169], v167, off offset:1024
	global_store_short v[168:169], v171, off offset:1088
	v_mul_f32_e32 v160, v110, v251
	v_mul_f32_e32 v161, v126, v251
	v_fma_f32 v160, v126, v243, -v160
	v_fmac_f32_e32 v161, v110, v243
	v_mul_f32_e32 v160, v166, v160
	v_mul_f32_e32 v161, v166, v161
	v_cvt_pk_bf16_f32 v160, v160, s0
	v_cvt_pk_bf16_f32 v161, v161, s0
	global_store_short v[168:169], v160, off offset:2048
	global_store_short v[168:169], v161, off offset:2112
	v_mul_f32_e32 v162, v111, v253
	v_mul_f32_e32 v164, v127, v253
	v_fma_f32 v162, v127, v244, -v162
	v_fmac_f32_e32 v164, v111, v244
	v_mul_f32_e32 v162, v166, v162
	v_mul_f32_e32 v164, v166, v164
	v_cvt_pk_bf16_f32 v162, v162, s0
	v_cvt_pk_bf16_f32 v164, v164, s0
	global_store_short v[168:169], v162, off offset:3072
	global_store_short v[168:169], v164, off offset:3136
	v_lshl_add_u64 v[168:169], v[168:169], 0, s[20:21]
	v_add_u32_e32 v170, 0x1000, v163
	global_load_dword v237, v170, s[4:5] offset:2048
	global_load_dword v245, v170, s[6:7] offset:2048
	global_load_dword v238, v170, s[4:5] offset:2176
	global_load_dword v246, v170, s[6:7] offset:2176
	global_load_dword v239, v170, s[4:5] offset:2304
	global_load_dword v247, v170, s[6:7] offset:2304
	global_load_dword v240, v170, s[4:5] offset:2432
	global_load_dword v248, v170, s[6:7] offset:2432
	global_load_dword v241, v170, s[4:5] offset:3072
	global_load_dword v249, v170, s[6:7] offset:3072
	global_load_dword v242, v170, s[4:5] offset:3200
	global_load_dword v250, v170, s[6:7] offset:3200
	global_load_dword v243, v170, s[4:5] offset:3328
	global_load_dword v251, v170, s[6:7] offset:3328
	global_load_dword v244, v170, s[4:5] offset:3456
	global_load_dword v253, v170, s[6:7] offset:3456
	s_waitcnt vmcnt(32)
	v_mul_f32_e32 v160, v64, v229
	v_mul_f32_e32 v161, v80, v229
	v_fma_f32 v160, v80, v221, -v160
	v_fmac_f32_e32 v161, v64, v221
	v_mul_f32_e32 v160, v166, v160
	v_mul_f32_e32 v161, v166, v161
	v_cvt_pk_bf16_f32 v160, v160, s0
	v_cvt_pk_bf16_f32 v161, v161, s0
	global_store_short v[168:169], v160, off
	global_store_short v[168:169], v161, off offset:64
	v_mul_f32_e32 v162, v65, v230
	v_mul_f32_e32 v164, v81, v230
	v_fma_f32 v162, v81, v222, -v162
	v_fmac_f32_e32 v164, v65, v222
	v_mul_f32_e32 v162, v166, v162
	v_mul_f32_e32 v164, v166, v164
	v_cvt_pk_bf16_f32 v162, v162, s0
	v_cvt_pk_bf16_f32 v164, v164, s0
	global_store_short v[168:169], v162, off offset:1024
	global_store_short v[168:169], v164, off offset:1088
	v_mul_f32_e32 v167, v66, v231
	v_mul_f32_e32 v171, v82, v231
	v_fma_f32 v167, v82, v223, -v167
	v_fmac_f32_e32 v171, v66, v223
	v_mul_f32_e32 v167, v166, v167
	v_mul_f32_e32 v171, v166, v171
	v_cvt_pk_bf16_f32 v167, v167, s0
	v_cvt_pk_bf16_f32 v171, v171, s0
	global_store_short v[168:169], v167, off offset:2048
	global_store_short v[168:169], v171, off offset:2112
	v_mul_f32_e32 v160, v67, v232
	v_mul_f32_e32 v161, v83, v232
	v_fma_f32 v160, v83, v224, -v160
	v_fmac_f32_e32 v161, v67, v224
	v_mul_f32_e32 v160, v166, v160
	v_mul_f32_e32 v161, v166, v161
	v_cvt_pk_bf16_f32 v160, v160, s0
	v_cvt_pk_bf16_f32 v161, v161, s0
	global_store_short v[168:169], v160, off offset:3072
	global_store_short v[168:169], v161, off offset:3136
	v_lshl_add_u64 v[168:169], v[168:169], 0, s[20:21]
	v_mul_f32_e32 v162, v68, v233
	v_mul_f32_e32 v164, v84, v233
	v_fma_f32 v162, v84, v225, -v162
	v_fmac_f32_e32 v164, v68, v225
	v_mul_f32_e32 v162, v166, v162
	v_mul_f32_e32 v164, v166, v164
	v_cvt_pk_bf16_f32 v162, v162, s0
	v_cvt_pk_bf16_f32 v164, v164, s0
	global_store_short v[168:169], v162, off
	global_store_short v[168:169], v164, off offset:64
	v_mul_f32_e32 v167, v69, v234
	v_mul_f32_e32 v171, v85, v234
	v_fma_f32 v167, v85, v226, -v167
	v_fmac_f32_e32 v171, v69, v226
	v_mul_f32_e32 v167, v166, v167
	v_mul_f32_e32 v171, v166, v171
	v_cvt_pk_bf16_f32 v167, v167, s0
	v_cvt_pk_bf16_f32 v171, v171, s0
	global_store_short v[168:169], v167, off offset:1024
	global_store_short v[168:169], v171, off offset:1088
	v_mul_f32_e32 v160, v70, v235
	v_mul_f32_e32 v161, v86, v235
	v_fma_f32 v160, v86, v227, -v160
	v_fmac_f32_e32 v161, v70, v227
	v_mul_f32_e32 v160, v166, v160
	v_mul_f32_e32 v161, v166, v161
	v_cvt_pk_bf16_f32 v160, v160, s0
	v_cvt_pk_bf16_f32 v161, v161, s0
	global_store_short v[168:169], v160, off offset:2048
	global_store_short v[168:169], v161, off offset:2112
	v_mul_f32_e32 v162, v71, v236
	v_mul_f32_e32 v164, v87, v236
	v_fma_f32 v162, v87, v228, -v162
	v_fmac_f32_e32 v164, v71, v228
	v_mul_f32_e32 v162, v166, v162
	v_mul_f32_e32 v164, v166, v164
	v_cvt_pk_bf16_f32 v162, v162, s0
	v_cvt_pk_bf16_f32 v164, v164, s0
	global_store_short v[168:169], v162, off offset:3072
	global_store_short v[168:169], v164, off offset:3136
	v_lshl_add_u64 v[168:169], v[168:169], 0, s[20:21]
	v_add_u32_e32 v170, 0x2000, v163
	global_load_dword v221, v170, s[4:5]
	global_load_dword v229, v170, s[6:7]
	global_load_dword v222, v170, s[4:5] offset:128
	global_load_dword v230, v170, s[6:7] offset:128
	global_load_dword v223, v170, s[4:5] offset:256
	global_load_dword v231, v170, s[6:7] offset:256
	global_load_dword v224, v170, s[4:5] offset:384
	global_load_dword v232, v170, s[6:7] offset:384
	global_load_dword v225, v170, s[4:5] offset:1024
	global_load_dword v233, v170, s[6:7] offset:1024
	global_load_dword v226, v170, s[4:5] offset:1152
	global_load_dword v234, v170, s[6:7] offset:1152
	global_load_dword v227, v170, s[4:5] offset:1280
	global_load_dword v235, v170, s[6:7] offset:1280
	global_load_dword v228, v170, s[4:5] offset:1408
	global_load_dword v236, v170, s[6:7] offset:1408
	s_waitcnt vmcnt(32)
	v_mul_f32_e32 v160, v72, v245
	v_mul_f32_e32 v161, v88, v245
	v_fma_f32 v160, v88, v237, -v160
	v_fmac_f32_e32 v161, v72, v237
	v_mul_f32_e32 v160, v166, v160
	v_mul_f32_e32 v161, v166, v161
	v_cvt_pk_bf16_f32 v160, v160, s0
	v_cvt_pk_bf16_f32 v161, v161, s0
	global_store_short v[168:169], v160, off
	global_store_short v[168:169], v161, off offset:64
	v_mul_f32_e32 v162, v73, v246
	v_mul_f32_e32 v164, v89, v246
	v_fma_f32 v162, v89, v238, -v162
	v_fmac_f32_e32 v164, v73, v238
	v_mul_f32_e32 v162, v166, v162
	v_mul_f32_e32 v164, v166, v164
	v_cvt_pk_bf16_f32 v162, v162, s0
	v_cvt_pk_bf16_f32 v164, v164, s0
	global_store_short v[168:169], v162, off offset:1024
	global_store_short v[168:169], v164, off offset:1088
	v_mul_f32_e32 v167, v74, v247
	v_mul_f32_e32 v171, v90, v247
	v_fma_f32 v167, v90, v239, -v167
	v_fmac_f32_e32 v171, v74, v239
	v_mul_f32_e32 v167, v166, v167
	v_mul_f32_e32 v171, v166, v171
	v_cvt_pk_bf16_f32 v167, v167, s0
	v_cvt_pk_bf16_f32 v171, v171, s0
	global_store_short v[168:169], v167, off offset:2048
	global_store_short v[168:169], v171, off offset:2112
	v_mul_f32_e32 v160, v75, v248
	v_mul_f32_e32 v161, v91, v248
	v_fma_f32 v160, v91, v240, -v160
	v_fmac_f32_e32 v161, v75, v240
	v_mul_f32_e32 v160, v166, v160
	v_mul_f32_e32 v161, v166, v161
	v_cvt_pk_bf16_f32 v160, v160, s0
	v_cvt_pk_bf16_f32 v161, v161, s0
	global_store_short v[168:169], v160, off offset:3072
	global_store_short v[168:169], v161, off offset:3136
	v_lshl_add_u64 v[168:169], v[168:169], 0, s[20:21]
	v_mul_f32_e32 v162, v76, v249
	v_mul_f32_e32 v164, v92, v249
	v_fma_f32 v162, v92, v241, -v162
	v_fmac_f32_e32 v164, v76, v241
	v_mul_f32_e32 v162, v166, v162
	v_mul_f32_e32 v164, v166, v164
	v_cvt_pk_bf16_f32 v162, v162, s0
	v_cvt_pk_bf16_f32 v164, v164, s0
	global_store_short v[168:169], v162, off
	global_store_short v[168:169], v164, off offset:64
	v_mul_f32_e32 v167, v77, v250
	v_mul_f32_e32 v171, v93, v250
	v_fma_f32 v167, v93, v242, -v167
	v_fmac_f32_e32 v171, v77, v242
	v_mul_f32_e32 v167, v166, v167
	v_mul_f32_e32 v171, v166, v171
	v_cvt_pk_bf16_f32 v167, v167, s0
	v_cvt_pk_bf16_f32 v171, v171, s0
	global_store_short v[168:169], v167, off offset:1024
	global_store_short v[168:169], v171, off offset:1088
	v_mul_f32_e32 v160, v78, v251
	v_mul_f32_e32 v161, v94, v251
	v_fma_f32 v160, v94, v243, -v160
	v_fmac_f32_e32 v161, v78, v243
	v_mul_f32_e32 v160, v166, v160
	v_mul_f32_e32 v161, v166, v161
	v_cvt_pk_bf16_f32 v160, v160, s0
	v_cvt_pk_bf16_f32 v161, v161, s0
	global_store_short v[168:169], v160, off offset:2048
	global_store_short v[168:169], v161, off offset:2112
	v_mul_f32_e32 v162, v79, v253
	v_mul_f32_e32 v164, v95, v253
	v_fma_f32 v162, v95, v244, -v162
	v_fmac_f32_e32 v164, v79, v244
	v_mul_f32_e32 v162, v166, v162
	v_mul_f32_e32 v164, v166, v164
	v_cvt_pk_bf16_f32 v162, v162, s0
	v_cvt_pk_bf16_f32 v164, v164, s0
	global_store_short v[168:169], v162, off offset:3072
	global_store_short v[168:169], v164, off offset:3136
	v_lshl_add_u64 v[168:169], v[168:169], 0, s[20:21]
	v_add_u32_e32 v170, 0x2000, v163
	global_load_dword v237, v170, s[4:5] offset:2048
	global_load_dword v245, v170, s[6:7] offset:2048
	global_load_dword v238, v170, s[4:5] offset:2176
	global_load_dword v246, v170, s[6:7] offset:2176
	global_load_dword v239, v170, s[4:5] offset:2304
	global_load_dword v247, v170, s[6:7] offset:2304
	global_load_dword v240, v170, s[4:5] offset:2432
	global_load_dword v248, v170, s[6:7] offset:2432
	global_load_dword v241, v170, s[4:5] offset:3072
	global_load_dword v249, v170, s[6:7] offset:3072
	global_load_dword v242, v170, s[4:5] offset:3200
	global_load_dword v250, v170, s[6:7] offset:3200
	global_load_dword v243, v170, s[4:5] offset:3328
	global_load_dword v251, v170, s[6:7] offset:3328
	global_load_dword v244, v170, s[4:5] offset:3456
	global_load_dword v253, v170, s[6:7] offset:3456
	s_waitcnt vmcnt(32)
	v_mul_f32_e32 v160, v32, v229
	v_mul_f32_e32 v161, v48, v229
	v_fma_f32 v160, v48, v221, -v160
	v_fmac_f32_e32 v161, v32, v221
	v_mul_f32_e32 v160, v166, v160
	v_mul_f32_e32 v161, v166, v161
	v_cvt_pk_bf16_f32 v160, v160, s0
	v_cvt_pk_bf16_f32 v161, v161, s0
	global_store_short v[168:169], v160, off
	global_store_short v[168:169], v161, off offset:64
	v_mul_f32_e32 v162, v33, v230
	v_mul_f32_e32 v164, v49, v230
	v_fma_f32 v162, v49, v222, -v162
	v_fmac_f32_e32 v164, v33, v222
	v_mul_f32_e32 v162, v166, v162
	v_mul_f32_e32 v164, v166, v164
	v_cvt_pk_bf16_f32 v162, v162, s0
	v_cvt_pk_bf16_f32 v164, v164, s0
	global_store_short v[168:169], v162, off offset:1024
	global_store_short v[168:169], v164, off offset:1088
	v_mul_f32_e32 v167, v34, v231
	v_mul_f32_e32 v171, v50, v231
	v_fma_f32 v167, v50, v223, -v167
	v_fmac_f32_e32 v171, v34, v223
	v_mul_f32_e32 v167, v166, v167
	v_mul_f32_e32 v171, v166, v171
	v_cvt_pk_bf16_f32 v167, v167, s0
	v_cvt_pk_bf16_f32 v171, v171, s0
	global_store_short v[168:169], v167, off offset:2048
	global_store_short v[168:169], v171, off offset:2112
	v_mul_f32_e32 v160, v35, v232
	v_mul_f32_e32 v161, v51, v232
	v_fma_f32 v160, v51, v224, -v160
	v_fmac_f32_e32 v161, v35, v224
	v_mul_f32_e32 v160, v166, v160
	v_mul_f32_e32 v161, v166, v161
	v_cvt_pk_bf16_f32 v160, v160, s0
	v_cvt_pk_bf16_f32 v161, v161, s0
	global_store_short v[168:169], v160, off offset:3072
	global_store_short v[168:169], v161, off offset:3136
	v_lshl_add_u64 v[168:169], v[168:169], 0, s[20:21]
	v_mul_f32_e32 v162, v36, v233
	v_mul_f32_e32 v164, v52, v233
	v_fma_f32 v162, v52, v225, -v162
	v_fmac_f32_e32 v164, v36, v225
	v_mul_f32_e32 v162, v166, v162
	v_mul_f32_e32 v164, v166, v164
	v_cvt_pk_bf16_f32 v162, v162, s0
	v_cvt_pk_bf16_f32 v164, v164, s0
	global_store_short v[168:169], v162, off
	global_store_short v[168:169], v164, off offset:64
	v_mul_f32_e32 v167, v37, v234
	v_mul_f32_e32 v171, v53, v234
	v_fma_f32 v167, v53, v226, -v167
	v_fmac_f32_e32 v171, v37, v226
	v_mul_f32_e32 v167, v166, v167
	v_mul_f32_e32 v171, v166, v171
	v_cvt_pk_bf16_f32 v167, v167, s0
	v_cvt_pk_bf16_f32 v171, v171, s0
	global_store_short v[168:169], v167, off offset:1024
	global_store_short v[168:169], v171, off offset:1088
	v_mul_f32_e32 v160, v38, v235
	v_mul_f32_e32 v161, v54, v235
	v_fma_f32 v160, v54, v227, -v160
	v_fmac_f32_e32 v161, v38, v227
	v_mul_f32_e32 v160, v166, v160
	v_mul_f32_e32 v161, v166, v161
	v_cvt_pk_bf16_f32 v160, v160, s0
	v_cvt_pk_bf16_f32 v161, v161, s0
	global_store_short v[168:169], v160, off offset:2048
	global_store_short v[168:169], v161, off offset:2112
	v_mul_f32_e32 v162, v39, v236
	v_mul_f32_e32 v164, v55, v236
	v_fma_f32 v162, v55, v228, -v162
	v_fmac_f32_e32 v164, v39, v228
	v_mul_f32_e32 v162, v166, v162
	v_mul_f32_e32 v164, v166, v164
	v_cvt_pk_bf16_f32 v162, v162, s0
	v_cvt_pk_bf16_f32 v164, v164, s0
	global_store_short v[168:169], v162, off offset:3072
	global_store_short v[168:169], v164, off offset:3136
	v_lshl_add_u64 v[168:169], v[168:169], 0, s[20:21]
	v_add_u32_e32 v170, 0x3000, v163
	global_load_dword v221, v170, s[4:5]
	global_load_dword v229, v170, s[6:7]
	global_load_dword v222, v170, s[4:5] offset:128
	global_load_dword v230, v170, s[6:7] offset:128
	global_load_dword v223, v170, s[4:5] offset:256
	global_load_dword v231, v170, s[6:7] offset:256
	global_load_dword v224, v170, s[4:5] offset:384
	global_load_dword v232, v170, s[6:7] offset:384
	global_load_dword v225, v170, s[4:5] offset:1024
	global_load_dword v233, v170, s[6:7] offset:1024
	global_load_dword v226, v170, s[4:5] offset:1152
	global_load_dword v234, v170, s[6:7] offset:1152
	global_load_dword v227, v170, s[4:5] offset:1280
	global_load_dword v235, v170, s[6:7] offset:1280
	global_load_dword v228, v170, s[4:5] offset:1408
	global_load_dword v236, v170, s[6:7] offset:1408
	s_waitcnt vmcnt(32)
	v_mul_f32_e32 v160, v40, v245
	v_mul_f32_e32 v161, v56, v245
	v_fma_f32 v160, v56, v237, -v160
	v_fmac_f32_e32 v161, v40, v237
	v_mul_f32_e32 v160, v166, v160
	v_mul_f32_e32 v161, v166, v161
	v_cvt_pk_bf16_f32 v160, v160, s0
	v_cvt_pk_bf16_f32 v161, v161, s0
	global_store_short v[168:169], v160, off
	global_store_short v[168:169], v161, off offset:64
	v_mul_f32_e32 v162, v41, v246
	v_mul_f32_e32 v164, v57, v246
	v_fma_f32 v162, v57, v238, -v162
	v_fmac_f32_e32 v164, v41, v238
	v_mul_f32_e32 v162, v166, v162
	v_mul_f32_e32 v164, v166, v164
	v_cvt_pk_bf16_f32 v162, v162, s0
	v_cvt_pk_bf16_f32 v164, v164, s0
	global_store_short v[168:169], v162, off offset:1024
	global_store_short v[168:169], v164, off offset:1088
	v_mul_f32_e32 v167, v42, v247
	v_mul_f32_e32 v171, v58, v247
	v_fma_f32 v167, v58, v239, -v167
	v_fmac_f32_e32 v171, v42, v239
	v_mul_f32_e32 v167, v166, v167
	v_mul_f32_e32 v171, v166, v171
	v_cvt_pk_bf16_f32 v167, v167, s0
	v_cvt_pk_bf16_f32 v171, v171, s0
	global_store_short v[168:169], v167, off offset:2048
	global_store_short v[168:169], v171, off offset:2112
	v_mul_f32_e32 v160, v43, v248
	v_mul_f32_e32 v161, v59, v248
	v_fma_f32 v160, v59, v240, -v160
	v_fmac_f32_e32 v161, v43, v240
	v_mul_f32_e32 v160, v166, v160
	v_mul_f32_e32 v161, v166, v161
	v_cvt_pk_bf16_f32 v160, v160, s0
	v_cvt_pk_bf16_f32 v161, v161, s0
	global_store_short v[168:169], v160, off offset:3072
	global_store_short v[168:169], v161, off offset:3136
	v_lshl_add_u64 v[168:169], v[168:169], 0, s[20:21]
	v_mul_f32_e32 v162, v44, v249
	v_mul_f32_e32 v164, v60, v249
	v_fma_f32 v162, v60, v241, -v162
	v_fmac_f32_e32 v164, v44, v241
	v_mul_f32_e32 v162, v166, v162
	v_mul_f32_e32 v164, v166, v164
	v_cvt_pk_bf16_f32 v162, v162, s0
	v_cvt_pk_bf16_f32 v164, v164, s0
	global_store_short v[168:169], v162, off
	global_store_short v[168:169], v164, off offset:64
	v_mul_f32_e32 v167, v45, v250
	v_mul_f32_e32 v171, v61, v250
	v_fma_f32 v167, v61, v242, -v167
	v_fmac_f32_e32 v171, v45, v242
	v_mul_f32_e32 v167, v166, v167
	v_mul_f32_e32 v171, v166, v171
	v_cvt_pk_bf16_f32 v167, v167, s0
	v_cvt_pk_bf16_f32 v171, v171, s0
	global_store_short v[168:169], v167, off offset:1024
	global_store_short v[168:169], v171, off offset:1088
	v_mul_f32_e32 v160, v46, v251
	v_mul_f32_e32 v161, v62, v251
	v_fma_f32 v160, v62, v243, -v160
	v_fmac_f32_e32 v161, v46, v243
	v_mul_f32_e32 v160, v166, v160
	v_mul_f32_e32 v161, v166, v161
	v_cvt_pk_bf16_f32 v160, v160, s0
	v_cvt_pk_bf16_f32 v161, v161, s0
	global_store_short v[168:169], v160, off offset:2048
	global_store_short v[168:169], v161, off offset:2112
	v_mul_f32_e32 v162, v47, v253
	v_mul_f32_e32 v164, v63, v253
	v_fma_f32 v162, v63, v244, -v162
	v_fmac_f32_e32 v164, v47, v244
	v_mul_f32_e32 v162, v166, v162
	v_mul_f32_e32 v164, v166, v164
	v_cvt_pk_bf16_f32 v162, v162, s0
	v_cvt_pk_bf16_f32 v164, v164, s0
	global_store_short v[168:169], v162, off offset:3072
	global_store_short v[168:169], v164, off offset:3136
	v_lshl_add_u64 v[168:169], v[168:169], 0, s[20:21]
	v_add_u32_e32 v170, 0x3000, v163
	global_load_dword v237, v170, s[4:5] offset:2048
	global_load_dword v245, v170, s[6:7] offset:2048
	global_load_dword v238, v170, s[4:5] offset:2176
	global_load_dword v246, v170, s[6:7] offset:2176
	global_load_dword v239, v170, s[4:5] offset:2304
	global_load_dword v247, v170, s[6:7] offset:2304
	global_load_dword v240, v170, s[4:5] offset:2432
	global_load_dword v248, v170, s[6:7] offset:2432
	global_load_dword v241, v170, s[4:5] offset:3072
	global_load_dword v249, v170, s[6:7] offset:3072
	global_load_dword v242, v170, s[4:5] offset:3200
	global_load_dword v250, v170, s[6:7] offset:3200
	global_load_dword v243, v170, s[4:5] offset:3328
	global_load_dword v251, v170, s[6:7] offset:3328
	global_load_dword v244, v170, s[4:5] offset:3456
	global_load_dword v253, v170, s[6:7] offset:3456
	s_waitcnt vmcnt(32)
	v_mul_f32_e32 v160, v0, v229
	v_mul_f32_e32 v161, v16, v229
	v_fma_f32 v160, v16, v221, -v160
	v_fmac_f32_e32 v161, v0, v221
	v_mul_f32_e32 v160, v166, v160
	v_mul_f32_e32 v161, v166, v161
	v_cvt_pk_bf16_f32 v160, v160, s0
	v_cvt_pk_bf16_f32 v161, v161, s0
	global_store_short v[168:169], v160, off
	global_store_short v[168:169], v161, off offset:64
	v_mul_f32_e32 v162, v1, v230
	v_mul_f32_e32 v164, v17, v230
	v_fma_f32 v162, v17, v222, -v162
	v_fmac_f32_e32 v164, v1, v222
	v_mul_f32_e32 v162, v166, v162
	v_mul_f32_e32 v164, v166, v164
	v_cvt_pk_bf16_f32 v162, v162, s0
	v_cvt_pk_bf16_f32 v164, v164, s0
	global_store_short v[168:169], v162, off offset:1024
	global_store_short v[168:169], v164, off offset:1088
	v_mul_f32_e32 v167, v2, v231
	v_mul_f32_e32 v171, v18, v231
	v_fma_f32 v167, v18, v223, -v167
	v_fmac_f32_e32 v171, v2, v223
	v_mul_f32_e32 v167, v166, v167
	v_mul_f32_e32 v171, v166, v171
	v_cvt_pk_bf16_f32 v167, v167, s0
	v_cvt_pk_bf16_f32 v171, v171, s0
	global_store_short v[168:169], v167, off offset:2048
	global_store_short v[168:169], v171, off offset:2112
	v_mul_f32_e32 v160, v3, v232
	v_mul_f32_e32 v161, v19, v232
	v_fma_f32 v160, v19, v224, -v160
	v_fmac_f32_e32 v161, v3, v224
	v_mul_f32_e32 v160, v166, v160
	v_mul_f32_e32 v161, v166, v161
	v_cvt_pk_bf16_f32 v160, v160, s0
	v_cvt_pk_bf16_f32 v161, v161, s0
	global_store_short v[168:169], v160, off offset:3072
	global_store_short v[168:169], v161, off offset:3136
	v_lshl_add_u64 v[168:169], v[168:169], 0, s[20:21]
	v_mul_f32_e32 v162, v4, v233
	v_mul_f32_e32 v164, v20, v233
	v_fma_f32 v162, v20, v225, -v162
	v_fmac_f32_e32 v164, v4, v225
	v_mul_f32_e32 v162, v166, v162
	v_mul_f32_e32 v164, v166, v164
	v_cvt_pk_bf16_f32 v162, v162, s0
	v_cvt_pk_bf16_f32 v164, v164, s0
	global_store_short v[168:169], v162, off
	global_store_short v[168:169], v164, off offset:64
	v_mul_f32_e32 v167, v5, v234
	v_mul_f32_e32 v171, v21, v234
	v_fma_f32 v167, v21, v226, -v167
	v_fmac_f32_e32 v171, v5, v226
	v_mul_f32_e32 v167, v166, v167
	v_mul_f32_e32 v171, v166, v171
	v_cvt_pk_bf16_f32 v167, v167, s0
	v_cvt_pk_bf16_f32 v171, v171, s0
	global_store_short v[168:169], v167, off offset:1024
	global_store_short v[168:169], v171, off offset:1088
	v_mul_f32_e32 v160, v6, v235
	v_mul_f32_e32 v161, v22, v235
	v_fma_f32 v160, v22, v227, -v160
	v_fmac_f32_e32 v161, v6, v227
	v_mul_f32_e32 v160, v166, v160
	v_mul_f32_e32 v161, v166, v161
	v_cvt_pk_bf16_f32 v160, v160, s0
	v_cvt_pk_bf16_f32 v161, v161, s0
	global_store_short v[168:169], v160, off offset:2048
	global_store_short v[168:169], v161, off offset:2112
	v_mul_f32_e32 v162, v7, v236
	v_mul_f32_e32 v164, v23, v236
	v_fma_f32 v162, v23, v228, -v162
	v_fmac_f32_e32 v164, v7, v228
	v_mul_f32_e32 v162, v166, v162
	v_mul_f32_e32 v164, v166, v164
	v_cvt_pk_bf16_f32 v162, v162, s0
	v_cvt_pk_bf16_f32 v164, v164, s0
	global_store_short v[168:169], v162, off offset:3072
	global_store_short v[168:169], v164, off offset:3136
	v_lshl_add_u64 v[168:169], v[168:169], 0, s[20:21]
	s_waitcnt vmcnt(16)
	v_mul_f32_e32 v160, v8, v245
	v_mul_f32_e32 v161, v24, v245
	v_fma_f32 v160, v24, v237, -v160
	v_fmac_f32_e32 v161, v8, v237
	v_mul_f32_e32 v160, v166, v160
	v_mul_f32_e32 v161, v166, v161
	v_cvt_pk_bf16_f32 v160, v160, s0
	v_cvt_pk_bf16_f32 v161, v161, s0
	global_store_short v[168:169], v160, off
	global_store_short v[168:169], v161, off offset:64
	v_mul_f32_e32 v162, v9, v246
	v_mul_f32_e32 v164, v25, v246
	v_fma_f32 v162, v25, v238, -v162
	v_fmac_f32_e32 v164, v9, v238
	v_mul_f32_e32 v162, v166, v162
	v_mul_f32_e32 v164, v166, v164
	v_cvt_pk_bf16_f32 v162, v162, s0
	v_cvt_pk_bf16_f32 v164, v164, s0
	global_store_short v[168:169], v162, off offset:1024
	global_store_short v[168:169], v164, off offset:1088
	v_mul_f32_e32 v167, v10, v247
	v_mul_f32_e32 v171, v26, v247
	v_fma_f32 v167, v26, v239, -v167
	v_fmac_f32_e32 v171, v10, v239
	v_mul_f32_e32 v167, v166, v167
	v_mul_f32_e32 v171, v166, v171
	v_cvt_pk_bf16_f32 v167, v167, s0
	v_cvt_pk_bf16_f32 v171, v171, s0
	global_store_short v[168:169], v167, off offset:2048
	global_store_short v[168:169], v171, off offset:2112
	v_mul_f32_e32 v160, v11, v248
	v_mul_f32_e32 v161, v27, v248
	v_fma_f32 v160, v27, v240, -v160
	v_fmac_f32_e32 v161, v11, v240
	v_mul_f32_e32 v160, v166, v160
	v_mul_f32_e32 v161, v166, v161
	v_cvt_pk_bf16_f32 v160, v160, s0
	v_cvt_pk_bf16_f32 v161, v161, s0
	global_store_short v[168:169], v160, off offset:3072
	global_store_short v[168:169], v161, off offset:3136
	v_lshl_add_u64 v[168:169], v[168:169], 0, s[20:21]
	v_mul_f32_e32 v162, v12, v249
	v_mul_f32_e32 v164, v28, v249
	v_fma_f32 v162, v28, v241, -v162
	v_fmac_f32_e32 v164, v12, v241
	v_mul_f32_e32 v162, v166, v162
	v_mul_f32_e32 v164, v166, v164
	v_cvt_pk_bf16_f32 v162, v162, s0
	v_cvt_pk_bf16_f32 v164, v164, s0
	global_store_short v[168:169], v162, off
	global_store_short v[168:169], v164, off offset:64
	v_mul_f32_e32 v167, v13, v250
	v_mul_f32_e32 v171, v29, v250
	v_fma_f32 v167, v29, v242, -v167
	v_fmac_f32_e32 v171, v13, v242
	v_mul_f32_e32 v167, v166, v167
	v_mul_f32_e32 v171, v166, v171
	v_cvt_pk_bf16_f32 v167, v167, s0
	v_cvt_pk_bf16_f32 v171, v171, s0
	global_store_short v[168:169], v167, off offset:1024
	global_store_short v[168:169], v171, off offset:1088
	v_mul_f32_e32 v160, v14, v251
	v_mul_f32_e32 v161, v30, v251
	v_fma_f32 v160, v30, v243, -v160
	v_fmac_f32_e32 v161, v14, v243
	v_mul_f32_e32 v160, v166, v160
	v_mul_f32_e32 v161, v166, v161
	v_cvt_pk_bf16_f32 v160, v160, s0
	v_cvt_pk_bf16_f32 v161, v161, s0
	global_store_short v[168:169], v160, off offset:2048
	global_store_short v[168:169], v161, off offset:2112
	v_mul_f32_e32 v162, v15, v253
	v_mul_f32_e32 v164, v31, v253
	v_fma_f32 v162, v31, v244, -v162
	v_fmac_f32_e32 v164, v15, v244
	v_mul_f32_e32 v162, v166, v162
	v_mul_f32_e32 v164, v166, v164
	v_cvt_pk_bf16_f32 v162, v162, s0
	v_cvt_pk_bf16_f32 v164, v164, s0
	global_store_short v[168:169], v162, off offset:3072
	global_store_short v[168:169], v164, off offset:3136
	s_mov_b64 s[20:21], -1
	s_andn2_b64 vcc, exec, s[16:17]
	s_mov_b64 s[16:17], -1
	s_cbranch_vccnz .LBB0_348

.LBB0_748:
	s_cmpk_lt_u32 s67, 0x200
	s_cselect_b64 vcc, -1, 0
	s_and_b64 s[14:15], vcc, exec
	s_cselect_b32 s8, 0, 0x1000000
	s_add_u32 s14, s86, s8
	s_addc_u32 s15, s87, 0
	v_lshl_or_b32 v162, v200, 2, v166
	v_lshlrev_b32_e32 v164, 1, v167
	v_lshl_add_u64 v[160:161], s[14:15], 0, v[164:165]
	v_cndmask_b32_e32 v166, 1.0, v194, vcc
	v_lshlrev_b32_e32 v164, 1, v199
	v_ashrrev_i32_e32 v163, 31, v162
	v_lshlrev_b64 v[168:169], 10, v[162:163]
	v_lshl_add_u64 v[168:169], v[160:161], 0, v[168:169]
	v_lshl_add_u64 v[168:169], v[168:169], 0, v[164:165]
	s_mov_b32 s8, 0x3ffe0
	v_lshlrev_b32_e32 v163, 5, v162
	v_and_or_b32 v163, v163, s8, v199
	v_lshlrev_b32_e32 v163, 2, v163
	s_mov_b32 s14, 0x2000
	s_mov_b32 s15, 0
	global_load_dword v221, v163, s[4:5]
	global_load_dword v229, v163, s[6:7]
	global_load_dword v222, v163, s[4:5] offset:128
	global_load_dword v230, v163, s[6:7] offset:128
	global_load_dword v223, v163, s[4:5] offset:256
	global_load_dword v231, v163, s[6:7] offset:256
	global_load_dword v224, v163, s[4:5] offset:384
	global_load_dword v232, v163, s[6:7] offset:384
	global_load_dword v225, v163, s[4:5] offset:1024
	global_load_dword v233, v163, s[6:7] offset:1024
	global_load_dword v226, v163, s[4:5] offset:1152
	global_load_dword v234, v163, s[6:7] offset:1152
	global_load_dword v227, v163, s[4:5] offset:1280
	global_load_dword v235, v163, s[6:7] offset:1280
	global_load_dword v228, v163, s[4:5] offset:1408
	global_load_dword v236, v163, s[6:7] offset:1408
	global_load_dword v237, v163, s[4:5] offset:2048
	global_load_dword v245, v163, s[6:7] offset:2048
	global_load_dword v238, v163, s[4:5] offset:2176
	global_load_dword v246, v163, s[6:7] offset:2176
	global_load_dword v239, v163, s[4:5] offset:2304
	global_load_dword v247, v163, s[6:7] offset:2304
	global_load_dword v240, v163, s[4:5] offset:2432
	global_load_dword v248, v163, s[6:7] offset:2432
	global_load_dword v241, v163, s[4:5] offset:3072
	global_load_dword v249, v163, s[6:7] offset:3072
	global_load_dword v242, v163, s[4:5] offset:3200
	global_load_dword v250, v163, s[6:7] offset:3200
	global_load_dword v243, v163, s[4:5] offset:3328
	global_load_dword v251, v163, s[6:7] offset:3328
	global_load_dword v244, v163, s[4:5] offset:3456
	global_load_dword v253, v163, s[6:7] offset:3456
	s_waitcnt vmcnt(16)
	v_mul_f32_e32 v160, v96, v229
	v_mul_f32_e32 v161, v112, v229
	v_fma_f32 v160, v112, v221, -v160
	v_fmac_f32_e32 v161, v96, v221
	v_mul_f32_e32 v160, v166, v160
	v_mul_f32_e32 v161, v166, v161
	v_cvt_pk_bf16_f32 v160, v160, s0
	v_cvt_pk_bf16_f32 v161, v161, s0
	global_store_short v[168:169], v160, off
	global_store_short v[168:169], v161, off offset:64
	v_mul_f32_e32 v162, v97, v230
	v_mul_f32_e32 v164, v113, v230
	v_fma_f32 v162, v113, v222, -v162
	v_fmac_f32_e32 v164, v97, v222
	v_mul_f32_e32 v162, v166, v162
	v_mul_f32_e32 v164, v166, v164
	v_cvt_pk_bf16_f32 v162, v162, s0
	v_cvt_pk_bf16_f32 v164, v164, s0
	global_store_short v[168:169], v162, off offset:1024
	global_store_short v[168:169], v164, off offset:1088
	v_mul_f32_e32 v167, v98, v231
	v_mul_f32_e32 v171, v114, v231
	v_fma_f32 v167, v114, v223, -v167
	v_fmac_f32_e32 v171, v98, v223
	v_mul_f32_e32 v167, v166, v167
	v_mul_f32_e32 v171, v166, v171
	v_cvt_pk_bf16_f32 v167, v167, s0
	v_cvt_pk_bf16_f32 v171, v171, s0
	global_store_short v[168:169], v167, off offset:2048
	global_store_short v[168:169], v171, off offset:2112
	v_mul_f32_e32 v160, v99, v232
	v_mul_f32_e32 v161, v115, v232
	v_fma_f32 v160, v115, v224, -v160
	v_fmac_f32_e32 v161, v99, v224
	v_mul_f32_e32 v160, v166, v160
	v_mul_f32_e32 v161, v166, v161
	v_cvt_pk_bf16_f32 v160, v160, s0
	v_cvt_pk_bf16_f32 v161, v161, s0
	global_store_short v[168:169], v160, off offset:3072
	global_store_short v[168:169], v161, off offset:3136
	v_lshl_add_u64 v[168:169], v[168:169], 0, s[14:15]
	v_mul_f32_e32 v162, v100, v233
	v_mul_f32_e32 v164, v116, v233
	v_fma_f32 v162, v116, v225, -v162
	v_fmac_f32_e32 v164, v100, v225
	v_mul_f32_e32 v162, v166, v162
	v_mul_f32_e32 v164, v166, v164
	v_cvt_pk_bf16_f32 v162, v162, s0
	v_cvt_pk_bf16_f32 v164, v164, s0
	global_store_short v[168:169], v162, off
	global_store_short v[168:169], v164, off offset:64
	v_mul_f32_e32 v167, v101, v234
	v_mul_f32_e32 v171, v117, v234
	v_fma_f32 v167, v117, v226, -v167
	v_fmac_f32_e32 v171, v101, v226
	v_mul_f32_e32 v167, v166, v167
	v_mul_f32_e32 v171, v166, v171
	v_cvt_pk_bf16_f32 v167, v167, s0
	v_cvt_pk_bf16_f32 v171, v171, s0
	global_store_short v[168:169], v167, off offset:1024
	global_store_short v[168:169], v171, off offset:1088
	v_mul_f32_e32 v160, v102, v235
	v_mul_f32_e32 v161, v118, v235
	v_fma_f32 v160, v118, v227, -v160
	v_fmac_f32_e32 v161, v102, v227
	v_mul_f32_e32 v160, v166, v160
	v_mul_f32_e32 v161, v166, v161
	v_cvt_pk_bf16_f32 v160, v160, s0
	v_cvt_pk_bf16_f32 v161, v161, s0
	global_store_short v[168:169], v160, off offset:2048
	global_store_short v[168:169], v161, off offset:2112
	v_mul_f32_e32 v162, v103, v236
	v_mul_f32_e32 v164, v119, v236
	v_fma_f32 v162, v119, v228, -v162
	v_fmac_f32_e32 v164, v103, v228
	v_mul_f32_e32 v162, v166, v162
	v_mul_f32_e32 v164, v166, v164
	v_cvt_pk_bf16_f32 v162, v162, s0
	v_cvt_pk_bf16_f32 v164, v164, s0
	global_store_short v[168:169], v162, off offset:3072
	global_store_short v[168:169], v164, off offset:3136
	v_lshl_add_u64 v[168:169], v[168:169], 0, s[14:15]
	v_add_u32_e32 v170, 0x1000, v163
	global_load_dword v221, v170, s[4:5]
	global_load_dword v229, v170, s[6:7]
	global_load_dword v222, v170, s[4:5] offset:128
	global_load_dword v230, v170, s[6:7] offset:128
	global_load_dword v223, v170, s[4:5] offset:256
	global_load_dword v231, v170, s[6:7] offset:256
	global_load_dword v224, v170, s[4:5] offset:384
	global_load_dword v232, v170, s[6:7] offset:384
	global_load_dword v225, v170, s[4:5] offset:1024
	global_load_dword v233, v170, s[6:7] offset:1024
	global_load_dword v226, v170, s[4:5] offset:1152
	global_load_dword v234, v170, s[6:7] offset:1152
	global_load_dword v227, v170, s[4:5] offset:1280
	global_load_dword v235, v170, s[6:7] offset:1280
	global_load_dword v228, v170, s[4:5] offset:1408
	global_load_dword v236, v170, s[6:7] offset:1408
	s_waitcnt vmcnt(32)
	v_mul_f32_e32 v160, v104, v245
	v_mul_f32_e32 v161, v120, v245
	v_fma_f32 v160, v120, v237, -v160
	v_fmac_f32_e32 v161, v104, v237
	v_mul_f32_e32 v160, v166, v160
	v_mul_f32_e32 v161, v166, v161
	v_cvt_pk_bf16_f32 v160, v160, s0
	v_cvt_pk_bf16_f32 v161, v161, s0
	global_store_short v[168:169], v160, off
	global_store_short v[168:169], v161, off offset:64
	v_mul_f32_e32 v162, v105, v246
	v_mul_f32_e32 v164, v121, v246
	v_fma_f32 v162, v121, v238, -v162
	v_fmac_f32_e32 v164, v105, v238
	v_mul_f32_e32 v162, v166, v162
	v_mul_f32_e32 v164, v166, v164
	v_cvt_pk_bf16_f32 v162, v162, s0
	v_cvt_pk_bf16_f32 v164, v164, s0
	global_store_short v[168:169], v162, off offset:1024
	global_store_short v[168:169], v164, off offset:1088
	v_mul_f32_e32 v167, v106, v247
	v_mul_f32_e32 v171, v122, v247
	v_fma_f32 v167, v122, v239, -v167
	v_fmac_f32_e32 v171, v106, v239
	v_mul_f32_e32 v167, v166, v167
	v_mul_f32_e32 v171, v166, v171
	v_cvt_pk_bf16_f32 v167, v167, s0
	v_cvt_pk_bf16_f32 v171, v171, s0
	global_store_short v[168:169], v167, off offset:2048
	global_store_short v[168:169], v171, off offset:2112
	v_mul_f32_e32 v160, v107, v248
	v_mul_f32_e32 v161, v123, v248
	v_fma_f32 v160, v123, v240, -v160
	v_fmac_f32_e32 v161, v107, v240
	v_mul_f32_e32 v160, v166, v160
	v_mul_f32_e32 v161, v166, v161
	v_cvt_pk_bf16_f32 v160, v160, s0
	v_cvt_pk_bf16_f32 v161, v161, s0
	global_store_short v[168:169], v160, off offset:3072
	global_store_short v[168:169], v161, off offset:3136
	v_lshl_add_u64 v[168:169], v[168:169], 0, s[14:15]
	v_mul_f32_e32 v162, v108, v249
	v_mul_f32_e32 v164, v124, v249
	v_fma_f32 v162, v124, v241, -v162
	v_fmac_f32_e32 v164, v108, v241
	v_mul_f32_e32 v162, v166, v162
	v_mul_f32_e32 v164, v166, v164
	v_cvt_pk_bf16_f32 v162, v162, s0
	v_cvt_pk_bf16_f32 v164, v164, s0
	global_store_short v[168:169], v162, off
	global_store_short v[168:169], v164, off offset:64
	v_mul_f32_e32 v167, v109, v250
	v_mul_f32_e32 v171, v125, v250
	v_fma_f32 v167, v125, v242, -v167
	v_fmac_f32_e32 v171, v109, v242
	v_mul_f32_e32 v167, v166, v167
	v_mul_f32_e32 v171, v166, v171
	v_cvt_pk_bf16_f32 v167, v167, s0
	v_cvt_pk_bf16_f32 v171, v171, s0
	global_store_short v[168:169], v167, off offset:1024
	global_store_short v[168:169], v171, off offset:1088
	v_mul_f32_e32 v160, v110, v251
	v_mul_f32_e32 v161, v126, v251
	v_fma_f32 v160, v126, v243, -v160
	v_fmac_f32_e32 v161, v110, v243
	v_mul_f32_e32 v160, v166, v160
	v_mul_f32_e32 v161, v166, v161
	v_cvt_pk_bf16_f32 v160, v160, s0
	v_cvt_pk_bf16_f32 v161, v161, s0
	global_store_short v[168:169], v160, off offset:2048
	global_store_short v[168:169], v161, off offset:2112
	v_mul_f32_e32 v162, v111, v253
	v_mul_f32_e32 v164, v127, v253
	v_fma_f32 v162, v127, v244, -v162
	v_fmac_f32_e32 v164, v111, v244
	v_mul_f32_e32 v162, v166, v162
	v_mul_f32_e32 v164, v166, v164
	v_cvt_pk_bf16_f32 v162, v162, s0
	v_cvt_pk_bf16_f32 v164, v164, s0
	global_store_short v[168:169], v162, off offset:3072
	global_store_short v[168:169], v164, off offset:3136
	v_lshl_add_u64 v[168:169], v[168:169], 0, s[14:15]
	v_add_u32_e32 v170, 0x1000, v163
	global_load_dword v237, v170, s[4:5] offset:2048
	global_load_dword v245, v170, s[6:7] offset:2048
	global_load_dword v238, v170, s[4:5] offset:2176
	global_load_dword v246, v170, s[6:7] offset:2176
	global_load_dword v239, v170, s[4:5] offset:2304
	global_load_dword v247, v170, s[6:7] offset:2304
	global_load_dword v240, v170, s[4:5] offset:2432
	global_load_dword v248, v170, s[6:7] offset:2432
	global_load_dword v241, v170, s[4:5] offset:3072
	global_load_dword v249, v170, s[6:7] offset:3072
	global_load_dword v242, v170, s[4:5] offset:3200
	global_load_dword v250, v170, s[6:7] offset:3200
	global_load_dword v243, v170, s[4:5] offset:3328
	global_load_dword v251, v170, s[6:7] offset:3328
	global_load_dword v244, v170, s[4:5] offset:3456
	global_load_dword v253, v170, s[6:7] offset:3456
	s_waitcnt vmcnt(32)
	v_mul_f32_e32 v160, v64, v229
	v_mul_f32_e32 v161, v80, v229
	v_fma_f32 v160, v80, v221, -v160
	v_fmac_f32_e32 v161, v64, v221
	v_mul_f32_e32 v160, v166, v160
	v_mul_f32_e32 v161, v166, v161
	v_cvt_pk_bf16_f32 v160, v160, s0
	v_cvt_pk_bf16_f32 v161, v161, s0
	global_store_short v[168:169], v160, off
	global_store_short v[168:169], v161, off offset:64
	v_mul_f32_e32 v162, v65, v230
	v_mul_f32_e32 v164, v81, v230
	v_fma_f32 v162, v81, v222, -v162
	v_fmac_f32_e32 v164, v65, v222
	v_mul_f32_e32 v162, v166, v162
	v_mul_f32_e32 v164, v166, v164
	v_cvt_pk_bf16_f32 v162, v162, s0
	v_cvt_pk_bf16_f32 v164, v164, s0
	global_store_short v[168:169], v162, off offset:1024
	global_store_short v[168:169], v164, off offset:1088
	v_mul_f32_e32 v167, v66, v231
	v_mul_f32_e32 v171, v82, v231
	v_fma_f32 v167, v82, v223, -v167
	v_fmac_f32_e32 v171, v66, v223
	v_mul_f32_e32 v167, v166, v167
	v_mul_f32_e32 v171, v166, v171
	v_cvt_pk_bf16_f32 v167, v167, s0
	v_cvt_pk_bf16_f32 v171, v171, s0
	global_store_short v[168:169], v167, off offset:2048
	global_store_short v[168:169], v171, off offset:2112
	v_mul_f32_e32 v160, v67, v232
	v_mul_f32_e32 v161, v83, v232
	v_fma_f32 v160, v83, v224, -v160
	v_fmac_f32_e32 v161, v67, v224
	v_mul_f32_e32 v160, v166, v160
	v_mul_f32_e32 v161, v166, v161
	v_cvt_pk_bf16_f32 v160, v160, s0
	v_cvt_pk_bf16_f32 v161, v161, s0
	global_store_short v[168:169], v160, off offset:3072
	global_store_short v[168:169], v161, off offset:3136
	v_lshl_add_u64 v[168:169], v[168:169], 0, s[14:15]
	v_mul_f32_e32 v162, v68, v233
	v_mul_f32_e32 v164, v84, v233
	v_fma_f32 v162, v84, v225, -v162
	v_fmac_f32_e32 v164, v68, v225
	v_mul_f32_e32 v162, v166, v162
	v_mul_f32_e32 v164, v166, v164
	v_cvt_pk_bf16_f32 v162, v162, s0
	v_cvt_pk_bf16_f32 v164, v164, s0
	global_store_short v[168:169], v162, off
	global_store_short v[168:169], v164, off offset:64
	v_mul_f32_e32 v167, v69, v234
	v_mul_f32_e32 v171, v85, v234
	v_fma_f32 v167, v85, v226, -v167
	v_fmac_f32_e32 v171, v69, v226
	v_mul_f32_e32 v167, v166, v167
	v_mul_f32_e32 v171, v166, v171
	v_cvt_pk_bf16_f32 v167, v167, s0
	v_cvt_pk_bf16_f32 v171, v171, s0
	global_store_short v[168:169], v167, off offset:1024
	global_store_short v[168:169], v171, off offset:1088
	v_mul_f32_e32 v160, v70, v235
	v_mul_f32_e32 v161, v86, v235
	v_fma_f32 v160, v86, v227, -v160
	v_fmac_f32_e32 v161, v70, v227
	v_mul_f32_e32 v160, v166, v160
	v_mul_f32_e32 v161, v166, v161
	v_cvt_pk_bf16_f32 v160, v160, s0
	v_cvt_pk_bf16_f32 v161, v161, s0
	global_store_short v[168:169], v160, off offset:2048
	global_store_short v[168:169], v161, off offset:2112
	v_mul_f32_e32 v162, v71, v236
	v_mul_f32_e32 v164, v87, v236
	v_fma_f32 v162, v87, v228, -v162
	v_fmac_f32_e32 v164, v71, v228
	v_mul_f32_e32 v162, v166, v162
	v_mul_f32_e32 v164, v166, v164
	v_cvt_pk_bf16_f32 v162, v162, s0
	v_cvt_pk_bf16_f32 v164, v164, s0
	global_store_short v[168:169], v162, off offset:3072
	global_store_short v[168:169], v164, off offset:3136
	v_lshl_add_u64 v[168:169], v[168:169], 0, s[14:15]
	v_add_u32_e32 v170, 0x2000, v163
	global_load_dword v221, v170, s[4:5]
	global_load_dword v229, v170, s[6:7]
	global_load_dword v222, v170, s[4:5] offset:128
	global_load_dword v230, v170, s[6:7] offset:128
	global_load_dword v223, v170, s[4:5] offset:256
	global_load_dword v231, v170, s[6:7] offset:256
	global_load_dword v224, v170, s[4:5] offset:384
	global_load_dword v232, v170, s[6:7] offset:384
	global_load_dword v225, v170, s[4:5] offset:1024
	global_load_dword v233, v170, s[6:7] offset:1024
	global_load_dword v226, v170, s[4:5] offset:1152
	global_load_dword v234, v170, s[6:7] offset:1152
	global_load_dword v227, v170, s[4:5] offset:1280
	global_load_dword v235, v170, s[6:7] offset:1280
	global_load_dword v228, v170, s[4:5] offset:1408
	global_load_dword v236, v170, s[6:7] offset:1408
	s_waitcnt vmcnt(32)
	v_mul_f32_e32 v160, v72, v245
	v_mul_f32_e32 v161, v88, v245
	v_fma_f32 v160, v88, v237, -v160
	v_fmac_f32_e32 v161, v72, v237
	v_mul_f32_e32 v160, v166, v160
	v_mul_f32_e32 v161, v166, v161
	v_cvt_pk_bf16_f32 v160, v160, s0
	v_cvt_pk_bf16_f32 v161, v161, s0
	global_store_short v[168:169], v160, off
	global_store_short v[168:169], v161, off offset:64
	v_mul_f32_e32 v162, v73, v246
	v_mul_f32_e32 v164, v89, v246
	v_fma_f32 v162, v89, v238, -v162
	v_fmac_f32_e32 v164, v73, v238
	v_mul_f32_e32 v162, v166, v162
	v_mul_f32_e32 v164, v166, v164
	v_cvt_pk_bf16_f32 v162, v162, s0
	v_cvt_pk_bf16_f32 v164, v164, s0
	global_store_short v[168:169], v162, off offset:1024
	global_store_short v[168:169], v164, off offset:1088
	v_mul_f32_e32 v167, v74, v247
	v_mul_f32_e32 v171, v90, v247
	v_fma_f32 v167, v90, v239, -v167
	v_fmac_f32_e32 v171, v74, v239
	v_mul_f32_e32 v167, v166, v167
	v_mul_f32_e32 v171, v166, v171
	v_cvt_pk_bf16_f32 v167, v167, s0
	v_cvt_pk_bf16_f32 v171, v171, s0
	global_store_short v[168:169], v167, off offset:2048
	global_store_short v[168:169], v171, off offset:2112
	v_mul_f32_e32 v160, v75, v248
	v_mul_f32_e32 v161, v91, v248
	v_fma_f32 v160, v91, v240, -v160
	v_fmac_f32_e32 v161, v75, v240
	v_mul_f32_e32 v160, v166, v160
	v_mul_f32_e32 v161, v166, v161
	v_cvt_pk_bf16_f32 v160, v160, s0
	v_cvt_pk_bf16_f32 v161, v161, s0
	global_store_short v[168:169], v160, off offset:3072
	global_store_short v[168:169], v161, off offset:3136
	v_lshl_add_u64 v[168:169], v[168:169], 0, s[14:15]
	v_mul_f32_e32 v162, v76, v249
	v_mul_f32_e32 v164, v92, v249
	v_fma_f32 v162, v92, v241, -v162
	v_fmac_f32_e32 v164, v76, v241
	v_mul_f32_e32 v162, v166, v162
	v_mul_f32_e32 v164, v166, v164
	v_cvt_pk_bf16_f32 v162, v162, s0
	v_cvt_pk_bf16_f32 v164, v164, s0
	global_store_short v[168:169], v162, off
	global_store_short v[168:169], v164, off offset:64
	v_mul_f32_e32 v167, v77, v250
	v_mul_f32_e32 v171, v93, v250
	v_fma_f32 v167, v93, v242, -v167
	v_fmac_f32_e32 v171, v77, v242
	v_mul_f32_e32 v167, v166, v167
	v_mul_f32_e32 v171, v166, v171
	v_cvt_pk_bf16_f32 v167, v167, s0
	v_cvt_pk_bf16_f32 v171, v171, s0
	global_store_short v[168:169], v167, off offset:1024
	global_store_short v[168:169], v171, off offset:1088
	v_mul_f32_e32 v160, v78, v251
	v_mul_f32_e32 v161, v94, v251
	v_fma_f32 v160, v94, v243, -v160
	v_fmac_f32_e32 v161, v78, v243
	v_mul_f32_e32 v160, v166, v160
	v_mul_f32_e32 v161, v166, v161
	v_cvt_pk_bf16_f32 v160, v160, s0
	v_cvt_pk_bf16_f32 v161, v161, s0
	global_store_short v[168:169], v160, off offset:2048
	global_store_short v[168:169], v161, off offset:2112
	v_mul_f32_e32 v162, v79, v253
	v_mul_f32_e32 v164, v95, v253
	v_fma_f32 v162, v95, v244, -v162
	v_fmac_f32_e32 v164, v79, v244
	v_mul_f32_e32 v162, v166, v162
	v_mul_f32_e32 v164, v166, v164
	v_cvt_pk_bf16_f32 v162, v162, s0
	v_cvt_pk_bf16_f32 v164, v164, s0
	global_store_short v[168:169], v162, off offset:3072
	global_store_short v[168:169], v164, off offset:3136
	v_lshl_add_u64 v[168:169], v[168:169], 0, s[14:15]
	v_add_u32_e32 v170, 0x2000, v163
	global_load_dword v237, v170, s[4:5] offset:2048
	global_load_dword v245, v170, s[6:7] offset:2048
	global_load_dword v238, v170, s[4:5] offset:2176
	global_load_dword v246, v170, s[6:7] offset:2176
	global_load_dword v239, v170, s[4:5] offset:2304
	global_load_dword v247, v170, s[6:7] offset:2304
	global_load_dword v240, v170, s[4:5] offset:2432
	global_load_dword v248, v170, s[6:7] offset:2432
	global_load_dword v241, v170, s[4:5] offset:3072
	global_load_dword v249, v170, s[6:7] offset:3072
	global_load_dword v242, v170, s[4:5] offset:3200
	global_load_dword v250, v170, s[6:7] offset:3200
	global_load_dword v243, v170, s[4:5] offset:3328
	global_load_dword v251, v170, s[6:7] offset:3328
	global_load_dword v244, v170, s[4:5] offset:3456
	global_load_dword v253, v170, s[6:7] offset:3456
	s_waitcnt vmcnt(32)
	v_mul_f32_e32 v160, v32, v229
	v_mul_f32_e32 v161, v48, v229
	v_fma_f32 v160, v48, v221, -v160
	v_fmac_f32_e32 v161, v32, v221
	v_mul_f32_e32 v160, v166, v160
	v_mul_f32_e32 v161, v166, v161
	v_cvt_pk_bf16_f32 v160, v160, s0
	v_cvt_pk_bf16_f32 v161, v161, s0
	global_store_short v[168:169], v160, off
	global_store_short v[168:169], v161, off offset:64
	v_mul_f32_e32 v162, v33, v230
	v_mul_f32_e32 v164, v49, v230
	v_fma_f32 v162, v49, v222, -v162
	v_fmac_f32_e32 v164, v33, v222
	v_mul_f32_e32 v162, v166, v162
	v_mul_f32_e32 v164, v166, v164
	v_cvt_pk_bf16_f32 v162, v162, s0
	v_cvt_pk_bf16_f32 v164, v164, s0
	global_store_short v[168:169], v162, off offset:1024
	global_store_short v[168:169], v164, off offset:1088
	v_mul_f32_e32 v167, v34, v231
	v_mul_f32_e32 v171, v50, v231
	v_fma_f32 v167, v50, v223, -v167
	v_fmac_f32_e32 v171, v34, v223
	v_mul_f32_e32 v167, v166, v167
	v_mul_f32_e32 v171, v166, v171
	v_cvt_pk_bf16_f32 v167, v167, s0
	v_cvt_pk_bf16_f32 v171, v171, s0
	global_store_short v[168:169], v167, off offset:2048
	global_store_short v[168:169], v171, off offset:2112
	v_mul_f32_e32 v160, v35, v232
	v_mul_f32_e32 v161, v51, v232
	v_fma_f32 v160, v51, v224, -v160
	v_fmac_f32_e32 v161, v35, v224
	v_mul_f32_e32 v160, v166, v160
	v_mul_f32_e32 v161, v166, v161
	v_cvt_pk_bf16_f32 v160, v160, s0
	v_cvt_pk_bf16_f32 v161, v161, s0
	global_store_short v[168:169], v160, off offset:3072
	global_store_short v[168:169], v161, off offset:3136
	v_lshl_add_u64 v[168:169], v[168:169], 0, s[14:15]
	v_mul_f32_e32 v162, v36, v233
	v_mul_f32_e32 v164, v52, v233
	v_fma_f32 v162, v52, v225, -v162
	v_fmac_f32_e32 v164, v36, v225
	v_mul_f32_e32 v162, v166, v162
	v_mul_f32_e32 v164, v166, v164
	v_cvt_pk_bf16_f32 v162, v162, s0
	v_cvt_pk_bf16_f32 v164, v164, s0
	global_store_short v[168:169], v162, off
	global_store_short v[168:169], v164, off offset:64
	v_mul_f32_e32 v167, v37, v234
	v_mul_f32_e32 v171, v53, v234
	v_fma_f32 v167, v53, v226, -v167
	v_fmac_f32_e32 v171, v37, v226
	v_mul_f32_e32 v167, v166, v167
	v_mul_f32_e32 v171, v166, v171
	v_cvt_pk_bf16_f32 v167, v167, s0
	v_cvt_pk_bf16_f32 v171, v171, s0
	global_store_short v[168:169], v167, off offset:1024
	global_store_short v[168:169], v171, off offset:1088
	v_mul_f32_e32 v160, v38, v235
	v_mul_f32_e32 v161, v54, v235
	v_fma_f32 v160, v54, v227, -v160
	v_fmac_f32_e32 v161, v38, v227
	v_mul_f32_e32 v160, v166, v160
	v_mul_f32_e32 v161, v166, v161
	v_cvt_pk_bf16_f32 v160, v160, s0
	v_cvt_pk_bf16_f32 v161, v161, s0
	global_store_short v[168:169], v160, off offset:2048
	global_store_short v[168:169], v161, off offset:2112
	v_mul_f32_e32 v162, v39, v236
	v_mul_f32_e32 v164, v55, v236
	v_fma_f32 v162, v55, v228, -v162
	v_fmac_f32_e32 v164, v39, v228
	v_mul_f32_e32 v162, v166, v162
	v_mul_f32_e32 v164, v166, v164
	v_cvt_pk_bf16_f32 v162, v162, s0
	v_cvt_pk_bf16_f32 v164, v164, s0
	global_store_short v[168:169], v162, off offset:3072
	global_store_short v[168:169], v164, off offset:3136
	v_lshl_add_u64 v[168:169], v[168:169], 0, s[14:15]
	v_add_u32_e32 v170, 0x3000, v163
	global_load_dword v221, v170, s[4:5]
	global_load_dword v229, v170, s[6:7]
	global_load_dword v222, v170, s[4:5] offset:128
	global_load_dword v230, v170, s[6:7] offset:128
	global_load_dword v223, v170, s[4:5] offset:256
	global_load_dword v231, v170, s[6:7] offset:256
	global_load_dword v224, v170, s[4:5] offset:384
	global_load_dword v232, v170, s[6:7] offset:384
	global_load_dword v225, v170, s[4:5] offset:1024
	global_load_dword v233, v170, s[6:7] offset:1024
	global_load_dword v226, v170, s[4:5] offset:1152
	global_load_dword v234, v170, s[6:7] offset:1152
	global_load_dword v227, v170, s[4:5] offset:1280
	global_load_dword v235, v170, s[6:7] offset:1280
	global_load_dword v228, v170, s[4:5] offset:1408
	global_load_dword v236, v170, s[6:7] offset:1408
	s_waitcnt vmcnt(32)
	v_mul_f32_e32 v160, v40, v245
	v_mul_f32_e32 v161, v56, v245
	v_fma_f32 v160, v56, v237, -v160
	v_fmac_f32_e32 v161, v40, v237
	v_mul_f32_e32 v160, v166, v160
	v_mul_f32_e32 v161, v166, v161
	v_cvt_pk_bf16_f32 v160, v160, s0
	v_cvt_pk_bf16_f32 v161, v161, s0
	global_store_short v[168:169], v160, off
	global_store_short v[168:169], v161, off offset:64
	v_mul_f32_e32 v162, v41, v246
	v_mul_f32_e32 v164, v57, v246
	v_fma_f32 v162, v57, v238, -v162
	v_fmac_f32_e32 v164, v41, v238
	v_mul_f32_e32 v162, v166, v162
	v_mul_f32_e32 v164, v166, v164
	v_cvt_pk_bf16_f32 v162, v162, s0
	v_cvt_pk_bf16_f32 v164, v164, s0
	global_store_short v[168:169], v162, off offset:1024
	global_store_short v[168:169], v164, off offset:1088
	v_mul_f32_e32 v167, v42, v247
	v_mul_f32_e32 v171, v58, v247
	v_fma_f32 v167, v58, v239, -v167
	v_fmac_f32_e32 v171, v42, v239
	v_mul_f32_e32 v167, v166, v167
	v_mul_f32_e32 v171, v166, v171
	v_cvt_pk_bf16_f32 v167, v167, s0
	v_cvt_pk_bf16_f32 v171, v171, s0
	global_store_short v[168:169], v167, off offset:2048
	global_store_short v[168:169], v171, off offset:2112
	v_mul_f32_e32 v160, v43, v248
	v_mul_f32_e32 v161, v59, v248
	v_fma_f32 v160, v59, v240, -v160
	v_fmac_f32_e32 v161, v43, v240
	v_mul_f32_e32 v160, v166, v160
	v_mul_f32_e32 v161, v166, v161
	v_cvt_pk_bf16_f32 v160, v160, s0
	v_cvt_pk_bf16_f32 v161, v161, s0
	global_store_short v[168:169], v160, off offset:3072
	global_store_short v[168:169], v161, off offset:3136
	v_lshl_add_u64 v[168:169], v[168:169], 0, s[14:15]
	v_mul_f32_e32 v162, v44, v249
	v_mul_f32_e32 v164, v60, v249
	v_fma_f32 v162, v60, v241, -v162
	v_fmac_f32_e32 v164, v44, v241
	v_mul_f32_e32 v162, v166, v162
	v_mul_f32_e32 v164, v166, v164
	v_cvt_pk_bf16_f32 v162, v162, s0
	v_cvt_pk_bf16_f32 v164, v164, s0
	global_store_short v[168:169], v162, off
	global_store_short v[168:169], v164, off offset:64
	v_mul_f32_e32 v167, v45, v250
	v_mul_f32_e32 v171, v61, v250
	v_fma_f32 v167, v61, v242, -v167
	v_fmac_f32_e32 v171, v45, v242
	v_mul_f32_e32 v167, v166, v167
	v_mul_f32_e32 v171, v166, v171
	v_cvt_pk_bf16_f32 v167, v167, s0
	v_cvt_pk_bf16_f32 v171, v171, s0
	global_store_short v[168:169], v167, off offset:1024
	global_store_short v[168:169], v171, off offset:1088
	v_mul_f32_e32 v160, v46, v251
	v_mul_f32_e32 v161, v62, v251
	v_fma_f32 v160, v62, v243, -v160
	v_fmac_f32_e32 v161, v46, v243
	v_mul_f32_e32 v160, v166, v160
	v_mul_f32_e32 v161, v166, v161
	v_cvt_pk_bf16_f32 v160, v160, s0
	v_cvt_pk_bf16_f32 v161, v161, s0
	global_store_short v[168:169], v160, off offset:2048
	global_store_short v[168:169], v161, off offset:2112
	v_mul_f32_e32 v162, v47, v253
	v_mul_f32_e32 v164, v63, v253
	v_fma_f32 v162, v63, v244, -v162
	v_fmac_f32_e32 v164, v47, v244
	v_mul_f32_e32 v162, v166, v162
	v_mul_f32_e32 v164, v166, v164
	v_cvt_pk_bf16_f32 v162, v162, s0
	v_cvt_pk_bf16_f32 v164, v164, s0
	global_store_short v[168:169], v162, off offset:3072
	global_store_short v[168:169], v164, off offset:3136
	v_lshl_add_u64 v[168:169], v[168:169], 0, s[14:15]
	v_add_u32_e32 v170, 0x3000, v163
	global_load_dword v237, v170, s[4:5] offset:2048
	global_load_dword v245, v170, s[6:7] offset:2048
	global_load_dword v238, v170, s[4:5] offset:2176
	global_load_dword v246, v170, s[6:7] offset:2176
	global_load_dword v239, v170, s[4:5] offset:2304
	global_load_dword v247, v170, s[6:7] offset:2304
	global_load_dword v240, v170, s[4:5] offset:2432
	global_load_dword v248, v170, s[6:7] offset:2432
	global_load_dword v241, v170, s[4:5] offset:3072
	global_load_dword v249, v170, s[6:7] offset:3072
	global_load_dword v242, v170, s[4:5] offset:3200
	global_load_dword v250, v170, s[6:7] offset:3200
	global_load_dword v243, v170, s[4:5] offset:3328
	global_load_dword v251, v170, s[6:7] offset:3328
	global_load_dword v244, v170, s[4:5] offset:3456
	global_load_dword v253, v170, s[6:7] offset:3456
	s_waitcnt vmcnt(32)
	v_mul_f32_e32 v160, v0, v229
	v_mul_f32_e32 v161, v16, v229
	v_fma_f32 v160, v16, v221, -v160
	v_fmac_f32_e32 v161, v0, v221
	v_mul_f32_e32 v160, v166, v160
	v_mul_f32_e32 v161, v166, v161
	v_cvt_pk_bf16_f32 v160, v160, s0
	v_cvt_pk_bf16_f32 v161, v161, s0
	global_store_short v[168:169], v160, off
	global_store_short v[168:169], v161, off offset:64
	v_mul_f32_e32 v162, v1, v230
	v_mul_f32_e32 v164, v17, v230
	v_fma_f32 v162, v17, v222, -v162
	v_fmac_f32_e32 v164, v1, v222
	v_mul_f32_e32 v162, v166, v162
	v_mul_f32_e32 v164, v166, v164
	v_cvt_pk_bf16_f32 v162, v162, s0
	v_cvt_pk_bf16_f32 v164, v164, s0
	global_store_short v[168:169], v162, off offset:1024
	global_store_short v[168:169], v164, off offset:1088
	v_mul_f32_e32 v167, v2, v231
	v_mul_f32_e32 v171, v18, v231
	v_fma_f32 v167, v18, v223, -v167
	v_fmac_f32_e32 v171, v2, v223
	v_mul_f32_e32 v167, v166, v167
	v_mul_f32_e32 v171, v166, v171
	v_cvt_pk_bf16_f32 v167, v167, s0
	v_cvt_pk_bf16_f32 v171, v171, s0
	global_store_short v[168:169], v167, off offset:2048
	global_store_short v[168:169], v171, off offset:2112
	v_mul_f32_e32 v160, v3, v232
	v_mul_f32_e32 v161, v19, v232
	v_fma_f32 v160, v19, v224, -v160
	v_fmac_f32_e32 v161, v3, v224
	v_mul_f32_e32 v160, v166, v160
	v_mul_f32_e32 v161, v166, v161
	v_cvt_pk_bf16_f32 v160, v160, s0
	v_cvt_pk_bf16_f32 v161, v161, s0
	global_store_short v[168:169], v160, off offset:3072
	global_store_short v[168:169], v161, off offset:3136
	v_lshl_add_u64 v[168:169], v[168:169], 0, s[14:15]
	v_mul_f32_e32 v162, v4, v233
	v_mul_f32_e32 v164, v20, v233
	v_fma_f32 v162, v20, v225, -v162
	v_fmac_f32_e32 v164, v4, v225
	v_mul_f32_e32 v162, v166, v162
	v_mul_f32_e32 v164, v166, v164
	v_cvt_pk_bf16_f32 v162, v162, s0
	v_cvt_pk_bf16_f32 v164, v164, s0
	global_store_short v[168:169], v162, off
	global_store_short v[168:169], v164, off offset:64
	v_mul_f32_e32 v167, v5, v234
	v_mul_f32_e32 v171, v21, v234
	v_fma_f32 v167, v21, v226, -v167
	v_fmac_f32_e32 v171, v5, v226
	v_mul_f32_e32 v167, v166, v167
	v_mul_f32_e32 v171, v166, v171
	v_cvt_pk_bf16_f32 v167, v167, s0
	v_cvt_pk_bf16_f32 v171, v171, s0
	global_store_short v[168:169], v167, off offset:1024
	global_store_short v[168:169], v171, off offset:1088
	v_mul_f32_e32 v160, v6, v235
	v_mul_f32_e32 v161, v22, v235
	v_fma_f32 v160, v22, v227, -v160
	v_fmac_f32_e32 v161, v6, v227
	v_mul_f32_e32 v160, v166, v160
	v_mul_f32_e32 v161, v166, v161
	v_cvt_pk_bf16_f32 v160, v160, s0
	v_cvt_pk_bf16_f32 v161, v161, s0
	global_store_short v[168:169], v160, off offset:2048
	global_store_short v[168:169], v161, off offset:2112
	v_mul_f32_e32 v162, v7, v236
	v_mul_f32_e32 v164, v23, v236
	v_fma_f32 v162, v23, v228, -v162
	v_fmac_f32_e32 v164, v7, v228
	v_mul_f32_e32 v162, v166, v162
	v_mul_f32_e32 v164, v166, v164
	v_cvt_pk_bf16_f32 v162, v162, s0
	v_cvt_pk_bf16_f32 v164, v164, s0
	global_store_short v[168:169], v162, off offset:3072
	global_store_short v[168:169], v164, off offset:3136
	v_lshl_add_u64 v[168:169], v[168:169], 0, s[14:15]
	s_waitcnt vmcnt(16)
	v_mul_f32_e32 v160, v8, v245
	v_mul_f32_e32 v161, v24, v245
	v_fma_f32 v160, v24, v237, -v160
	v_fmac_f32_e32 v161, v8, v237
	v_mul_f32_e32 v160, v166, v160
	v_mul_f32_e32 v161, v166, v161
	v_cvt_pk_bf16_f32 v160, v160, s0
	v_cvt_pk_bf16_f32 v161, v161, s0
	global_store_short v[168:169], v160, off
	global_store_short v[168:169], v161, off offset:64
	v_mul_f32_e32 v162, v9, v246
	v_mul_f32_e32 v164, v25, v246
	v_fma_f32 v162, v25, v238, -v162
	v_fmac_f32_e32 v164, v9, v238
	v_mul_f32_e32 v162, v166, v162
	v_mul_f32_e32 v164, v166, v164
	v_cvt_pk_bf16_f32 v162, v162, s0
	v_cvt_pk_bf16_f32 v164, v164, s0
	global_store_short v[168:169], v162, off offset:1024
	global_store_short v[168:169], v164, off offset:1088
	v_mul_f32_e32 v167, v10, v247
	v_mul_f32_e32 v171, v26, v247
	v_fma_f32 v167, v26, v239, -v167
	v_fmac_f32_e32 v171, v10, v239
	v_mul_f32_e32 v167, v166, v167
	v_mul_f32_e32 v171, v166, v171
	v_cvt_pk_bf16_f32 v167, v167, s0
	v_cvt_pk_bf16_f32 v171, v171, s0
	global_store_short v[168:169], v167, off offset:2048
	global_store_short v[168:169], v171, off offset:2112
	v_mul_f32_e32 v160, v11, v248
	v_mul_f32_e32 v161, v27, v248
	v_fma_f32 v160, v27, v240, -v160
	v_fmac_f32_e32 v161, v11, v240
	v_mul_f32_e32 v160, v166, v160
	v_mul_f32_e32 v161, v166, v161
	v_cvt_pk_bf16_f32 v160, v160, s0
	v_cvt_pk_bf16_f32 v161, v161, s0
	global_store_short v[168:169], v160, off offset:3072
	global_store_short v[168:169], v161, off offset:3136
	v_lshl_add_u64 v[168:169], v[168:169], 0, s[14:15]
	v_mul_f32_e32 v162, v12, v249
	v_mul_f32_e32 v164, v28, v249
	v_fma_f32 v162, v28, v241, -v162
	v_fmac_f32_e32 v164, v12, v241
	v_mul_f32_e32 v162, v166, v162
	v_mul_f32_e32 v164, v166, v164
	v_cvt_pk_bf16_f32 v162, v162, s0
	v_cvt_pk_bf16_f32 v164, v164, s0
	global_store_short v[168:169], v162, off
	global_store_short v[168:169], v164, off offset:64
	v_mul_f32_e32 v167, v13, v250
	v_mul_f32_e32 v171, v29, v250
	v_fma_f32 v167, v29, v242, -v167
	v_fmac_f32_e32 v171, v13, v242
	v_mul_f32_e32 v167, v166, v167
	v_mul_f32_e32 v171, v166, v171
	v_cvt_pk_bf16_f32 v167, v167, s0
	v_cvt_pk_bf16_f32 v171, v171, s0
	global_store_short v[168:169], v167, off offset:1024
	global_store_short v[168:169], v171, off offset:1088
	v_mul_f32_e32 v160, v14, v251
	v_mul_f32_e32 v161, v30, v251
	v_fma_f32 v160, v30, v243, -v160
	v_fmac_f32_e32 v161, v14, v243
	v_mul_f32_e32 v160, v166, v160
	v_mul_f32_e32 v161, v166, v161
	v_cvt_pk_bf16_f32 v160, v160, s0
	v_cvt_pk_bf16_f32 v161, v161, s0
	global_store_short v[168:169], v160, off offset:2048
	global_store_short v[168:169], v161, off offset:2112
	v_mul_f32_e32 v162, v15, v253
	v_mul_f32_e32 v164, v31, v253
	v_fma_f32 v162, v31, v244, -v162
	v_fmac_f32_e32 v164, v15, v244
	v_mul_f32_e32 v162, v166, v162
	v_mul_f32_e32 v164, v166, v164
	v_cvt_pk_bf16_f32 v162, v162, s0
	v_cvt_pk_bf16_f32 v164, v164, s0
	global_store_short v[168:169], v162, off offset:3072
	global_store_short v[168:169], v164, off offset:3136
	s_mov_b64 s[14:15], -1
	s_andn2_b64 vcc, exec, s[10:11]
	s_mov_b64 s[10:11], -1
	s_cbranch_vccnz .LBB0_731

	.amdhsa_kernel _Z4megaILb1EEv6Params
		.amdhsa_group_segment_fixed_size 16
		.amdhsa_private_segment_fixed_size 0
		.amdhsa_kernarg_size 472
		.amdhsa_user_sgpr_count 2
		.amdhsa_user_sgpr_dispatch_ptr 0
		.amdhsa_user_sgpr_queue_ptr 0
		.amdhsa_user_sgpr_kernarg_segment_ptr 1
		.amdhsa_user_sgpr_dispatch_id 0
		.amdhsa_user_sgpr_kernarg_preload_length 0
		.amdhsa_user_sgpr_kernarg_preload_offset 0
		.amdhsa_user_sgpr_private_segment_size 0
		.amdhsa_uses_dynamic_stack 0
		.amdhsa_enable_private_segment 0
		.amdhsa_system_sgpr_workgroup_id_x 1
		.amdhsa_system_sgpr_workgroup_id_y 0
		.amdhsa_system_sgpr_workgroup_id_z 0
		.amdhsa_system_sgpr_workgroup_info 0
		.amdhsa_system_vgpr_workitem_id 2
		.amdhsa_next_free_vgpr 256
		.amdhsa_next_free_sgpr 98
		.amdhsa_accum_offset 256
		.amdhsa_reserve_vcc 1
		.amdhsa_float_round_mode_32 0
		.amdhsa_float_round_mode_16_64 0
		.amdhsa_float_denorm_mode_32 3
		.amdhsa_float_denorm_mode_16_64 3
		.amdhsa_dx10_clamp 1
		.amdhsa_ieee_mode 1
		.amdhsa_fp16_overflow 0
		.amdhsa_tg_split 0
		.amdhsa_exception_fp_ieee_invalid_op 0
		.amdhsa_exception_fp_denorm_src 0
		.amdhsa_exception_fp_ieee_div_zero 0
		.amdhsa_exception_fp_ieee_overflow 0
		.amdhsa_exception_fp_ieee_underflow 0
		.amdhsa_exception_fp_ieee_inexact 0
		.amdhsa_exception_int_div_zero 0
	.end_amdhsa_kernel

amdhsa.kernels:
  - .agpr_count:     0
    .args:
      - .offset:         0
        .size:           216
        .value_kind:     by_value
      - .offset:         216
        .size:           4
        .value_kind:     hidden_block_count_x
      - .offset:         220
        .size:           4
        .value_kind:     hidden_block_count_y
      - .offset:         224
        .size:           4
        .value_kind:     hidden_block_count_z
      - .offset:         228
        .size:           2
        .value_kind:     hidden_group_size_x
      - .offset:         230
        .size:           2
        .value_kind:     hidden_group_size_y
      - .offset:         232
        .size:           2
        .value_kind:     hidden_group_size_z
      - .offset:         234
        .size:           2
        .value_kind:     hidden_remainder_x
      - .offset:         236
        .size:           2
        .value_kind:     hidden_remainder_y
      - .offset:         238
        .size:           2
        .value_kind:     hidden_remainder_z
      - .offset:         256
        .size:           8
        .value_kind:     hidden_global_offset_x
      - .offset:         264
        .size:           8
        .value_kind:     hidden_global_offset_y
      - .offset:         272
        .size:           8
        .value_kind:     hidden_global_offset_z
      - .offset:         280
        .size:           2
        .value_kind:     hidden_grid_dims
      - .offset:         304
        .size:           8
        .value_kind:     hidden_multigrid_sync_arg
      - .offset:         336
        .size:           4
        .value_kind:     hidden_dynamic_lds_size
    .group_segment_fixed_size: 16
    .kernarg_segment_align: 8
    .kernarg_segment_size: 472
    .language:       OpenCL C
    .language_version:
      - 2
      - 0
    .max_flat_workgroup_size: 512
    .name:           _Z4megaILb1EEv6Params
    .private_segment_fixed_size: 0
    .sgpr_count:     104
    .sgpr_spill_count: 75
    .symbol:         _Z4megaILb1EEv6Params.kd
    .uniform_work_group_size: 1
    .uses_dynamic_stack: false
    .vgpr_count:     256
    .vgpr_spill_count: 0
    .wavefront_size: 64
